# output phase: the two independent 4-wave halves staggered by one workgroup barrier (park segment of one half beside the MFMA/epilogue segment of the other)
# speedup vs baseline: 1.0164x; 1.0164x over previous
; __device__ __forceinline__ void phase_out(const Params& p, unsigned char* shm) {
;     ...
;     const int tid = threadIdx.x, lane = tid & 63, wid = tid >> 6, fr = lane & 15, fq = lane >> 4;
;     const int half = wid >> 2, nt = wid & 3, th = tid & 255, crow = th >> 3, cseg = (th & 7) * 8;
;     bf16_t* base = (bf16_t*)shm + half * 7 * TILE;
;     bf16_t* SbT = base; bf16_t* UTt = base + TILE; bf16_t* Qt = base + 2 * TILE; bf16_t* AQt = base + 3 * TILE; bf16_t* YVt = base + 4 * TILE; bf16_t* PVt = base + 5 * TILE; bf16_t* GBt = base + 6 * TILE;
;     u32x4 g[7][2];
;     auto gload = [&](int pr) {
;         const int item = 2 * pr + half, h = item & 15, row0 = (item >> 4) * 64; const size_t cb = (size_t)item * 4096;
; #pragma unroll
;         for (int i = 0; i < 2; ++i) { const int r = crow + 32 * i; const size_t o = cb + r * 64 + cseg;
;             g[0][i] = *(const u32x4*)(p.Z + (size_t)(row0 + r) * LDZ + ZC_S + h * 64 + cseg);
;             g[1][i] = *(const u32x4*)(p.UTG + o); g[2][i] = *(const u32x4*)(p.QG + o); g[3][i] = *(const u32x4*)(p.AQBG + o); g[4][i] = *(const u32x4*)(p.YVG + o);
;             g[5][i] = *(const u32x4*)(p.PV + ((size_t)(row0 + r) * 16 + h) * 64 + cseg);
;             g[6][i] = *(const u32x4*)(p.Z + (size_t)(row0 + r) * LDZ + ZC_GB + h * 64 + cseg); }
;     };
;     if ((int)blockIdx.x < NPAIR) gload(blockIdx.x);
.LBB0_496:
	s_or_b64 exec, exec, s[2:3]
	s_cmpk_gt_i32 s40, 0x10ff
	s_barrier
	s_cbranch_scc1 .LBB0_499
	s_load_dwordx2 s[2:3], s[0:1], 0xb8
	v_lshrrev_b32_e32 v109, 8, v133
	v_lshl_add_u32 v104, s40, 1, v109
	s_waitcnt vmcnt(2)
	v_lshlrev_b32_e32 v0, 2, v104
	v_and_b32_e32 v111, 31, v164
	v_and_b32_e32 v26, 0xffffffc0, v0
	v_or_b32_e32 v20, v26, v111
	s_movk_i32 s10, 0x3a00
	s_waitcnt lgkmcnt(0)
	v_mov_b64_e32 v[0:1], s[2:3]
	v_lshlrev_b32_e32 v2, 7, v104
	v_and_b32_e32 v56, 56, v131
	v_mov_b32_e32 v107, 0
	v_mad_i64_i32 v[0:1], s[4:5], v20, s10, v[0:1]
	v_and_b32_e32 v106, 0x780, v2
	v_lshlrev_b32_e32 v58, 1, v56
	v_mov_b32_e32 v59, v107
	v_lshl_add_u64 v[0:1], v[0:1], 0, v[106:107]
	v_lshl_add_u64 v[24:25], v[0:1], 0, v[58:59]
	s_movk_i32 s11, 0x1000
	v_add_co_u32_e32 v0, vcc, s11, v24
	v_ashrrev_i32_e32 v105, 31, v104
	s_nop 0
	v_addc_co_u32_e32 v1, vcc, 0, v25, vcc
	s_movk_i32 s20, 0x3000
	v_lshlrev_b64 v[32:33], 12, v[104:105]
	s_load_dwordx8 s[12:19], s[0:1], 0xe0
	v_add_co_u32_e32 v34, vcc, s20, v24
	v_or_b32_e32 v105, 32, v111
	s_nop 0
	v_addc_co_u32_e32 v35, vcc, 0, v25, vcc
	v_or_b32_e32 v48, v26, v105
	v_mov_b64_e32 v[24:25], s[2:3]
	s_load_dwordx2 s[4:5], s[0:1], 0x100
	s_load_dwordx2 s[6:7], s[0:1], 0x128
	v_mad_i64_i32 v[24:25], s[8:9], v48, s10, v[24:25]
	v_ashrrev_i32_e32 v21, 31, v20
	v_lshl_add_u64 v[24:25], v[24:25], 0, v[106:107]
	v_lshl_or_b32 v108, v111, 6, v56
	v_lshlrev_b64 v[20:21], 11, v[20:21]
	v_ashrrev_i32_e32 v49, 31, v48
	v_lshl_add_u64 v[52:53], v[24:25], 0, v[58:59]
	v_or_b32_e32 v4, v32, v108
	v_mov_b32_e32 v5, v33
	s_waitcnt lgkmcnt(0)
	v_lshl_add_u64 v[20:21], s[12:13], 0, v[20:21]
	v_lshl_or_b32 v110, v105, 6, v56
	v_add_co_u32_e32 v36, vcc, s11, v52
	v_lshlrev_b64 v[48:49], 11, v[48:49]
	v_lshlrev_b64 v[16:17], 1, v[4:5]
	v_lshl_add_u64 v[20:21], v[20:21], 0, v[106:107]
	v_or_b32_e32 v32, v32, v110
	v_addc_co_u32_e32 v37, vcc, 0, v53, vcc
	v_lshl_add_u64 v[48:49], s[12:13], 0, v[48:49]
	v_lshl_add_u64 v[4:5], s[4:5], 0, v[16:17]
	s_waitcnt vmcnt(0)
	v_lshl_add_u64 v[8:9], s[14:15], 0, v[16:17]
	v_lshl_add_u64 v[12:13], s[16:17], 0, v[16:17]
	v_lshl_add_u64 v[16:17], s[18:19], 0, v[16:17]
	v_lshl_add_u64 v[20:21], v[20:21], 0, v[58:59]
	v_lshlrev_b64 v[44:45], 1, v[32:33]
	v_lshl_add_u64 v[48:49], v[48:49], 0, v[106:107]
	v_add_co_u32_e32 v52, vcc, s20, v52
	global_load_dwordx4 v[0:3], v[0:1], off offset:2048
	v_lshl_add_u64 v[32:33], s[4:5], 0, v[44:45]
	global_load_dwordx4 v[4:7], v[4:5], off
	v_lshl_add_u64 v[40:41], s[16:17], 0, v[44:45]
	global_load_dwordx4 v[8:11], v[8:9], off
	v_lshl_add_u64 v[48:49], v[48:49], 0, v[58:59]
	global_load_dwordx4 v[12:15], v[12:13], off
	v_addc_co_u32_e32 v53, vcc, 0, v53, vcc
	global_load_dwordx4 v[16:19], v[16:17], off
	v_lshrrev_b32_e32 v60, 2, v133
	global_load_dwordx4 v[20:23], v[20:21], off
	s_nop 0
	global_load_dwordx4 v[24:27], v[34:35], off offset:256
	global_load_dwordx4 v[28:31], v[36:37], off offset:2048
	v_lshl_add_u64 v[36:37], s[14:15], 0, v[44:45]
	v_lshl_add_u64 v[44:45], s[18:19], 0, v[44:45]
	global_load_dwordx4 v[32:35], v[32:33], off
	s_load_dwordx4 s[24:27], s[0:1], 0x98
	global_load_dwordx4 v[36:39], v[36:37], off
	s_mov_b32 s8, 0xfc00
	global_load_dwordx4 v[40:43], v[40:41], off
	v_bfe_u32 v59, v133, 4, 2
	global_load_dwordx4 v[44:47], v[44:45], off
	v_and_or_b32 v119, v60, 48, v161
	global_load_dwordx4 v[48:51], v[48:49], off
	v_mad_u32_u24 v57, v109, s8, 0
	global_load_dwordx4 v[52:55], v[52:53], off offset:256
	v_mul_u32_u24_e32 v60, 0x90, v119
	v_lshlrev_b32_e32 v122, 3, v59
	v_lshlrev_b32_e32 v106, 4, v59
	v_add_u32_e32 v58, v57, v58
	v_add3_u32 v123, v57, v60, v122
	v_add_u32_e32 v57, v57, v106
	v_mul_u32_u24_e32 v59, 0x90, v111
	v_mul_u32_u24_e32 v60, 0x90, v161
	v_readlane_b32 s8, v244, 3
	s_waitcnt lgkmcnt(0)
	v_lshl_add_u64 v[112:113], s[24:25], 0, v[106:107]
	v_lshl_add_u64 v[114:115], s[26:27], 0, v[106:107]
	v_lshl_add_u32 v124, v109, 2, s8
	s_lshl_b32 s21, s38, 3
	s_lshl_b32 s22, s38, 1
	v_add_u32_e32 v125, v58, v59
	v_lshlrev_b32_e32 v116, 1, v56
	v_add_u32_e32 v126, v57, v60
	v_mov_b32_e32 v127, 0x3a27c5ac
	s_mov_b32 s23, 0x800000
	v_mbcnt_hi_u32_b32 v134, -1, v129
	s_mov_b32 s8, s40
	s_waitcnt vmcnt(0)
	v_readfirstlane_b32 s86, v133
	s_nop 3
	s_lshr_b32 s86, s86, 8
	s_cmp_eq_u32 s86, 0
	s_cbranch_scc1 .Lout_stag0
	s_barrier
; #define LDS_BARRIER() do { asm volatile("s_waitcnt lgkmcnt(0)" ::: "memory"); __builtin_amdgcn_s_barrier(); asm volatile("" ::: "memory"); } while (0)
; __device__ __forceinline__ void phase_out(const Params& p, unsigned char* shm) {
;     ...
;     auto gload = [&](int pr) {
;         const int item = 2 * pr + half, h = item & 15, row0 = (item >> 4) * 64; const size_t cb = (size_t)item * 4096;
; #pragma unroll
;         for (int i = 0; i < 2; ++i) { const int r = crow + 32 * i; const size_t o = cb + r * 64 + cseg;
;             g[0][i] = *(const u32x4*)(p.Z + (size_t)(row0 + r) * LDZ + ZC_S + h * 64 + cseg);
;             g[1][i] = *(const u32x4*)(p.UTG + o); g[2][i] = *(const u32x4*)(p.QG + o); g[3][i] = *(const u32x4*)(p.AQBG + o); g[4][i] = *(const u32x4*)(p.YVG + o);
;             g[5][i] = *(const u32x4*)(p.PV + ((size_t)(row0 + r) * 16 + h) * 64 + cseg);
;             g[6][i] = *(const u32x4*)(p.Z + (size_t)(row0 + r) * LDZ + ZC_GB + h * 64 + cseg); }
;     };
;     if ((int)blockIdx.x < NPAIR) gload(blockIdx.x);
;     for (int pr = blockIdx.x; pr < NPAIR; pr += gridDim.x) {
;         const int item = 2 * pr + half, h = item & 15, row0 = (item >> 4) * 64;
;         const float rk = p.PRK[(size_t)(row0 + 16 * nt + fr) * 16 + h];
;         f32x4 gng[4], gnb[4];
; #pragma unroll
;         for (int mv = 0; mv < 4; ++mv) { gng[mv] = *(const f32x4*)(p.gn_g + h * 64 + 16 * mv + 4 * fq); gnb[mv] = *(const f32x4*)(p.gn_b + h * 64 + 16 * mv + 4 * fq); }
; #pragma unroll
;         for (int a = 0; a < 7; ++a)
; #pragma unroll
;             for (int i = 0; i < 2; ++i) *(u32x4*)(base + a * TILE + (crow + 32 * i) * LD + cseg) = g[a][i];
;         { const int npr = pr + (int)gridDim.x; gload(npr < NPAIR ? npr : pr); }
;         LDS_BARRIER();
.Lout_stag0:
.LBB0_498:
	v_and_b32_e32 v135, 0xffffffc0, v124
	v_or_b32_e32 v56, v135, v119
	v_ashrrev_i32_e32 v57, 31, v56
	s_add_i32 s24, s8, s38
	v_and_b32_e32 v136, 15, v104
	v_lshlrev_b64 v[56:57], 6, v[56:57]
	s_cmpk_lt_i32 s24, 0x1100
	v_lshl_add_u64 v[56:57], s[6:7], 0, v[56:57]
	v_lshlrev_b32_e32 v106, 2, v136
	s_cselect_b64 s[26:27], -1, 0
	v_lshl_add_u64 v[56:57], v[56:57], 0, v[106:107]
	v_lshlrev_b32_e32 v106, 8, v136
	s_and_b64 vcc, s[26:27], exec
	global_load_dword v118, v[56:57], off
	v_lshl_add_u64 v[56:57], v[112:113], 0, v[106:107]
	v_lshl_add_u64 v[60:61], v[114:115], 0, v[106:107]
	s_cselect_b32 s8, s24, s8
	global_load_dwordx4 v[80:83], v[56:57], off
	global_load_dwordx4 v[84:87], v[60:61], off
	global_load_dwordx4 v[72:75], v[56:57], off offset:64
	global_load_dwordx4 v[76:79], v[60:61], off offset:64
	global_load_dwordx4 v[64:67], v[56:57], off offset:128
	global_load_dwordx4 v[68:71], v[60:61], off offset:128
	s_nop 0
	global_load_dwordx4 v[56:59], v[56:57], off offset:192
	s_nop 0
	global_load_dwordx4 v[60:63], v[60:61], off offset:192
	s_waitcnt vmcnt(24)
	ds_write_b128 v125, v[0:3]
	s_waitcnt vmcnt(17)
	ds_write_b128 v125, v[28:31] offset:4608
	ds_write_b128 v125, v[4:7] offset:9216
	s_waitcnt vmcnt(16)
	ds_write_b128 v125, v[32:35] offset:13824
	ds_write_b128 v125, v[8:11] offset:18432
	s_waitcnt vmcnt(15)
	ds_write_b128 v125, v[36:39] offset:23040
	ds_write_b128 v125, v[12:15] offset:27648
	s_waitcnt vmcnt(14)
	ds_write_b128 v125, v[40:43] offset:32256
	ds_write_b128 v125, v[16:19] offset:36864
	s_waitcnt vmcnt(13)
	ds_write_b128 v125, v[44:47] offset:41472
	ds_write_b128 v125, v[20:23] offset:46080
	s_waitcnt vmcnt(12)
	ds_write_b128 v125, v[48:51] offset:50688
	ds_write_b128 v125, v[24:27] offset:55296
	s_waitcnt vmcnt(11)
	ds_write_b128 v125, v[52:55] offset:59904
	v_lshl_add_u32 v0, s8, 1, v109
	v_lshlrev_b32_e32 v1, 2, v0
	v_and_b32_e32 v30, 0xffffffc0, v1
	v_ashrrev_i32_e32 v1, 31, v0
	v_lshlrev_b64 v[32:33], 12, v[0:1]
	v_or_b32_e32 v20, v30, v111
	v_mov_b64_e32 v[28:29], s[2:3]
	v_lshlrev_b32_e32 v0, 7, v0
	v_mad_i64_i32 v[2:3], s[8:9], v20, s10, v[28:29]
	v_and_b32_e32 v106, 0x780, v0
	v_mov_b32_e32 v117, v107
	v_lshl_add_u64 v[0:1], v[2:3], 0, v[106:107]
	v_lshl_add_u64 v[24:25], v[0:1], 0, v[116:117]
	v_add_co_u32_e64 v0, s[8:9], s11, v24
	v_or_b32_e32 v48, v30, v105
	s_nop 0
	v_addc_co_u32_e64 v1, s[8:9], 0, v25, s[8:9]
	v_add_co_u32_e64 v24, s[8:9], s20, v24
	v_ashrrev_i32_e32 v21, 31, v20
	s_nop 0
	v_addc_co_u32_e64 v25, s[8:9], 0, v25, s[8:9]
	v_mad_i64_i32 v[28:29], s[8:9], v48, s10, v[28:29]
	v_lshl_add_u64 v[28:29], v[28:29], 0, v[106:107]
	v_ashrrev_i32_e32 v49, 31, v48
	v_lshl_add_u64 v[52:53], v[28:29], 0, v[116:117]
	v_lshlrev_b64 v[20:21], 11, v[20:21]
	v_add_co_u32_e64 v28, s[8:9], s11, v52
	v_lshlrev_b64 v[48:49], 11, v[48:49]
	v_or_b32_e32 v4, v32, v108
	v_mov_b32_e32 v5, v33
	v_lshl_add_u64 v[20:21], s[12:13], 0, v[20:21]
	v_or_b32_e32 v32, v32, v110
	v_addc_co_u32_e64 v29, s[8:9], 0, v53, s[8:9]
	v_lshl_add_u64 v[48:49], s[12:13], 0, v[48:49]
	v_lshlrev_b64 v[16:17], 1, v[4:5]
	v_lshl_add_u64 v[20:21], v[20:21], 0, v[106:107]
	v_lshlrev_b64 v[44:45], 1, v[32:33]
	v_lshl_add_u64 v[48:49], v[48:49], 0, v[106:107]
	v_add_co_u32_e64 v52, s[8:9], s20, v52
	v_lshl_add_u64 v[4:5], s[4:5], 0, v[16:17]
	v_lshl_add_u64 v[8:9], s[14:15], 0, v[16:17]
	v_lshl_add_u64 v[12:13], s[16:17], 0, v[16:17]
	v_lshl_add_u64 v[16:17], s[18:19], 0, v[16:17]
	v_lshl_add_u64 v[20:21], v[20:21], 0, v[116:117]
	v_lshl_add_u64 v[32:33], s[4:5], 0, v[44:45]
	v_lshl_add_u64 v[36:37], s[14:15], 0, v[44:45]
	v_lshl_add_u64 v[40:41], s[16:17], 0, v[44:45]
	v_lshl_add_u64 v[44:45], s[18:19], 0, v[44:45]
	v_lshl_add_u64 v[48:49], v[48:49], 0, v[116:117]
	v_addc_co_u32_e64 v53, s[8:9], 0, v53, s[8:9]
	global_load_dwordx4 v[0:3], v[0:1], off offset:2048
	v_add_u32_e32 v106, 0x9000, v123
	global_load_dwordx4 v[4:7], v[4:5], off
	v_add_u32_e32 v120, v123, v122
	global_load_dwordx4 v[8:11], v[8:9], off
	v_and_b32_e32 v137, 64, v134
	global_load_dwordx4 v[12:15], v[12:13], off
	v_add_u32_e32 v137, 64, v137
	global_load_dwordx4 v[16:19], v[16:17], off
	v_add_u32_e32 v124, s21, v124
	global_load_dwordx4 v[20:23], v[20:21], off
	v_add_u32_e32 v104, s22, v104
	global_load_dwordx4 v[24:27], v[24:25], off offset:256
	s_nop 0
	global_load_dwordx4 v[28:31], v[28:29], off offset:2048
	s_nop 0
	global_load_dwordx4 v[32:35], v[32:33], off
	s_nop 0
	global_load_dwordx4 v[36:39], v[36:37], off
	s_nop 0
	global_load_dwordx4 v[40:43], v[40:41], off
	s_nop 0
	global_load_dwordx4 v[44:47], v[44:45], off
	s_nop 0
	global_load_dwordx4 v[48:51], v[48:49], off
	s_nop 0
	global_load_dwordx4 v[52:55], v[52:53], off offset:256
	s_waitcnt lgkmcnt(0)
	s_barrier
; __device__ __forceinline__ f32x4 ld_bf4(const bf16_t* p) { const u32x2 u = *(const u32x2*)p; return (f32x4){bf_lo(u.x), bf_hi(u.x), bf_lo(u.y), bf_hi(u.y)}; }
; #define MFMA16(a, b, c) __builtin_amdgcn_mfma_f32_16x16x32_bf16(a, b, c, 0, 0, 0)
; __device__ __forceinline__ void phase_out(const Params& p, unsigned char* shm) {
;     ...
;         const int trow = 16 * nt + fr;
;         f32x4 acc[4];
; #pragma unroll
;         for (int mv = 0; mv < 4; ++mv) acc[mv] = ld_bf4(YVt + trow * LD + 16 * mv + 4 * fq);
; #pragma unroll
;         for (int ks = 0; ks < 2; ++ks) {
;             const bf16x8 bq = ldfrag(Qt, LD, 16 * nt, 32 * ks, fr, fq), ba = ldfrag(AQt, LD, 16 * nt, 32 * ks, fr, fq);
; #pragma unroll
;             for (int mv = 0; mv < 4; ++mv) {
;                 acc[mv] = MFMA16(ldfrag(SbT, LD, 16 * mv, 32 * ks, fr, fq), bq, acc[mv]);
;                 acc[mv] = MFMA16(ldfrag(UTt, LD, 16 * mv, 32 * ks, fr, fq), ba, acc[mv]);
;             }
;         }
;         float s = 0.f;
; #pragma unroll
;         for (int mv = 0; mv < 4; ++mv) s += (acc[mv][0] + acc[mv][1]) + (acc[mv][2] + acc[mv][3]);
;         s += __shfl_xor(s, 16); s += __shfl_xor(s, 32);
;         const float mean = s * (1.0f / 64.0f);
;         float q = 0.f;
; #pragma unroll
;         for (int mv = 0; mv < 4; ++mv) { const f32x4 d = acc[mv] - mean; q += (d[0] * d[0] + d[1] * d[1]) + (d[2] * d[2] + d[3] * d[3]); }
;         q += __shfl_xor(q, 16); q += __shfl_xor(q, 32);
	ds_read2_b64 v[88:91], v106 offset1:4
	ds_read2_b64 v[96:99], v106 offset0:8 offset1:12
	ds_read_b128 v[138:141], v120 offset:18432
	ds_read_b128 v[142:145], v120 offset:27648
	ds_read_b128 v[146:149], v126
	s_waitcnt lgkmcnt(4)
	v_lshlrev_b32_e32 v92, 16, v88
	v_and_b32_e32 v93, 0xffff0000, v88
	v_lshlrev_b32_e32 v94, 16, v89
	v_and_b32_e32 v95, 0xffff0000, v89
	v_lshlrev_b32_e32 v88, 16, v90
	v_and_b32_e32 v89, 0xffff0000, v90
	s_waitcnt lgkmcnt(0)
	v_mfma_f32_16x16x32_bf16 v[92:95], v[146:149], v[138:141], v[92:95]
	ds_read_b128 v[146:149], v126 offset:9216
	v_lshlrev_b32_e32 v90, 16, v91
	v_and_b32_e32 v91, 0xffff0000, v91
	s_waitcnt lgkmcnt(0)
	v_mfma_f32_16x16x32_bf16 v[92:95], v[146:149], v[142:145], v[92:95]
	ds_read_b128 v[146:149], v126 offset:2304
	v_lshlrev_b32_e32 v100, 16, v96
	v_and_b32_e32 v101, 0xffff0000, v96
	s_waitcnt lgkmcnt(0)
	v_mfma_f32_16x16x32_bf16 v[88:91], v[146:149], v[138:141], v[88:91]
	ds_read_b128 v[146:149], v126 offset:11520
	v_lshlrev_b32_e32 v102, 16, v97
	v_and_b32_e32 v103, 0xffff0000, v97
	s_waitcnt lgkmcnt(0)
	v_mfma_f32_16x16x32_bf16 v[88:91], v[146:149], v[142:145], v[88:91]
	ds_read_b128 v[146:149], v126 offset:4608
	v_lshlrev_b32_e32 v96, 16, v98
	v_and_b32_e32 v97, 0xffff0000, v98
	s_waitcnt lgkmcnt(0)
	v_mfma_f32_16x16x32_bf16 v[100:103], v[146:149], v[138:141], v[100:103]
	ds_read_b128 v[146:149], v126 offset:13824
	v_lshlrev_b32_e32 v98, 16, v99
	v_and_b32_e32 v99, 0xffff0000, v99
	s_waitcnt lgkmcnt(0)
	v_mfma_f32_16x16x32_bf16 v[146:149], v[146:149], v[142:145], v[100:103]
	s_nop 2
	ds_read_b128 v[100:103], v126 offset:6912
	s_waitcnt lgkmcnt(0)
	v_mfma_f32_16x16x32_bf16 v[96:99], v[100:103], v[138:141], v[96:99]
	ds_read_b128 v[100:103], v126 offset:16128
	s_waitcnt lgkmcnt(0)
	v_mfma_f32_16x16x32_bf16 v[138:141], v[100:103], v[142:145], v[96:99]
	ds_read_b128 v[142:145], v120 offset:18496
	ds_read_b128 v[150:153], v120 offset:27712
	s_nop 2
	ds_read_b128 v[96:99], v126 offset:64
	s_waitcnt lgkmcnt(0)
	v_mfma_f32_16x16x32_bf16 v[92:95], v[96:99], v[142:145], v[92:95]
	ds_read_b128 v[96:99], v126 offset:9280
	s_waitcnt lgkmcnt(0)
	v_mfma_f32_16x16x32_bf16 v[100:103], v[96:99], v[150:153], v[92:95]
	s_nop 4
	ds_read_b128 v[92:95], v126 offset:2368
	s_nop 1
	v_mov_b32_e32 v120, v101
	s_waitcnt lgkmcnt(0)
	v_mfma_f32_16x16x32_bf16 v[88:91], v[92:95], v[142:145], v[88:91]
	ds_read_b128 v[92:95], v126 offset:11584
	v_mov_b32_e32 v121, v102
	s_waitcnt lgkmcnt(0)
	v_mfma_f32_16x16x32_bf16 v[96:99], v[92:95], v[150:153], v[88:91]
	s_nop 3
	ds_read_b128 v[88:91], v126 offset:4672
	ds_read_b128 v[92:95], v126 offset:13888
	s_waitcnt lgkmcnt(1)
	v_mfma_f32_16x16x32_bf16 v[88:91], v[88:91], v[142:145], v[146:149]
	s_waitcnt lgkmcnt(0)
	v_mfma_f32_16x16x32_bf16 v[92:95], v[92:95], v[150:153], v[88:91]
	s_nop 5
	ds_read_b128 v[88:91], v126 offset:6976
	s_waitcnt lgkmcnt(0)
	v_mfma_f32_16x16x32_bf16 v[88:91], v[88:91], v[142:145], v[138:141]
	s_nop 2
	ds_read_b128 v[138:141], v126 offset:16192
	v_add_f32_e32 v142, v94, v95
	s_waitcnt lgkmcnt(0)
	v_mfma_f32_16x16x32_bf16 v[88:91], v[138:141], v[150:153], v[88:91]
	v_mov_b32_e32 v138, v100
	v_mov_b32_e32 v139, v103
	v_pk_add_f32 v[120:121], v[120:121], v[138:139]
	v_mov_b32_e32 v138, v97
	v_mov_b32_e32 v139, v98
	v_mov_b32_e32 v140, v96
	v_mov_b32_e32 v141, v99
	v_pk_add_f32 v[138:139], v[138:139], v[140:141]
	v_add_f32_e32 v120, v120, v121
	v_pk_add_f32 v[138:139], v[138:139], v[138:139] op_sel:[0,1] op_sel_hi:[1,0]
	v_add_f32_e32 v120, 0, v120
	v_add_f32_e32 v140, v92, v93
	v_mov_b32_e32 v121, v88
	v_mov_b32_e32 v139, v89
	v_mov_b32_e32 v141, v90
	v_mov_b32_e32 v143, v91
	v_pk_add_f32 v[120:121], v[120:121], v[138:139]
	v_pk_add_f32 v[138:139], v[140:141], v[142:143]
	s_nop 0
	v_pk_add_f32 v[120:121], v[120:121], v[138:139]
	s_nop 0
	v_add_f32_e32 v120, v120, v121
	v_xor_b32_e32 v121, 16, v134
	v_cmp_lt_i32_e64 s[8:9], v121, v137
	s_nop 1
	v_cndmask_b32_e64 v121, v134, v121, s[8:9]
	v_lshlrev_b32_e32 v144, 2, v121
	ds_bpermute_b32 v121, v144, v120
	s_waitcnt lgkmcnt(0)
	v_add_f32_e32 v120, v120, v121
	v_xor_b32_e32 v121, 32, v134
	v_cmp_lt_i32_e64 s[8:9], v121, v137
	s_nop 1
	v_cndmask_b32_e64 v121, v134, v121, s[8:9]
	v_lshlrev_b32_e32 v137, 2, v121
	ds_bpermute_b32 v121, v137, v120
	s_waitcnt lgkmcnt(0)
	v_add_f32_e32 v145, v120, v121
	v_fmamk_f32 v121, v145, 0xbc800000, v101
	v_fmamk_f32 v120, v145, 0xbc800000, v100
	v_fmamk_f32 v103, v145, 0xbc800000, v103
	v_fmac_f32_e32 v102, 0xbc800000, v145
	v_pk_mul_f32 v[100:101], v[102:103], v[102:103]
	v_pk_mul_f32 v[138:139], v[120:121], v[120:121]
	v_fmamk_f32 v99, v145, 0xbc800000, v99
	v_pk_mov_b32 v[140:141], v[138:139], v[100:101] op_sel:[1,0]
	v_mov_b32_e32 v139, v101
	v_pk_add_f32 v[100:101], v[140:141], v[138:139]
	v_fmac_f32_e32 v98, 0xbc800000, v145
	v_pk_add_f32 v[138:139], v[100:101], v[100:101] op_sel_hi:[0,1]
	v_fmamk_f32 v101, v145, 0xbc800000, v97
	v_fmamk_f32 v100, v145, 0xbc800000, v96
	v_pk_mul_f32 v[96:97], v[98:99], v[98:99]
	v_pk_mul_f32 v[140:141], v[100:101], v[100:101]
	v_fmac_f32_e32 v94, 0xbc800000, v145
	v_pk_mov_b32 v[142:143], v[140:141], v[96:97] op_sel:[1,0]
	v_mov_b32_e32 v141, v97
	v_pk_add_f32 v[96:97], v[142:143], v[140:141]
	v_fmamk_f32 v95, v145, 0xbc800000, v95
	v_pk_add_f32 v[140:141], v[96:97], v[96:97] op_sel_hi:[0,1]
	v_fmamk_f32 v96, v145, 0xbc800000, v92
	v_fmamk_f32 v97, v145, 0xbc800000, v93
	v_mul_f32_e32 v92, v96, v96
	v_pk_fma_f32 v[92:93], v[96:97], v[96:97], v[92:93] op_sel_hi:[1,1,0]
	v_fmamk_f32 v91, v145, 0xbc800000, v91
	v_mul_f32_e32 v92, v94, v94
	v_pk_fma_f32 v[142:143], v[94:95], v[94:95], v[92:93] op_sel_hi:[1,1,0]
	v_fmamk_f32 v90, v145, 0xbc800000, v90
	v_fmamk_f32 v89, v145, 0xbc800000, v89
	v_fmac_f32_e32 v88, 0xbc800000, v145
	v_mul_f32_e32 v92, v88, v88
	v_mul_f32_e32 v142, v89, v89
	v_mul_f32_e32 v138, v90, v90
	v_mul_f32_e32 v140, v91, v91
	v_pk_add_f32 v[92:93], v[92:93], v[142:143]
	v_pk_add_f32 v[138:139], v[138:139], v[140:141]
	s_nop 0
	v_pk_add_f32 v[92:93], v[92:93], v[138:139]
	s_nop 0
	v_add_f32_e32 v92, v92, v93
	ds_bpermute_b32 v93, v144, v92
	s_waitcnt lgkmcnt(0)
; __device__ __forceinline__ float silu_f(float x) { return x * __builtin_amdgcn_rcpf(1.0f + __builtin_amdgcn_exp2f(-1.44269504089f * x)); }
; __device__ __forceinline__ f32x4 ld_bf4(const bf16_t* p) { const u32x2 u = *(const u32x2*)p; return (f32x4){bf_lo(u.x), bf_hi(u.x), bf_lo(u.y), bf_hi(u.y)}; }
; __device__ __forceinline__ void st_bf4(bf16_t* p, f32x4 v) { u32x2 u; u.x = pk_bf16(v[0], v[1]); u.y = pk_bf16(v[2], v[3]); *(u32x2*)p = u; }
; #define LDS_BARRIER() do { asm volatile("s_waitcnt lgkmcnt(0)" ::: "memory"); __builtin_amdgcn_s_barrier(); asm volatile("" ::: "memory"); } while (0)
; __device__ __forceinline__ void phase_out(const Params& p, unsigned char* shm) {
;     ...
;         q += __shfl_xor(q, 16); q += __shfl_xor(q, 32);
;         const float rstd = rsqrtf(q * (1.0f / 64.0f) + 64e-5f);
; #pragma unroll
;         for (int mv = 0; mv < 4; ++mv) {
;             const int vch = 16 * mv + 4 * fq;
;             const f32x4 vmx = ld_bf4(PVt + trow * LD + vch), gb = ld_bf4(GBt + trow * LD + vch);
;             f32x4 o = (acc[mv] - mean) * rstd * gng[mv] + gnb[mv] + rk * vmx;
; #pragma unroll
;             for (int e = 0; e < 4; ++e) o[e] *= silu_f(gb[e]);
;             st_bf4(YVt + trow * LD + vch, o);
;         }
;         LDS_BARRIER();
	v_add_f32_e32 v92, v92, v93
	ds_bpermute_b32 v93, v137, v92
	v_add_u32_e32 v137, 0xd800, v123
	ds_read2_b64 v[142:145], v137 offset1:4
	s_waitcnt lgkmcnt(1)
	v_add_f32_e32 v92, v92, v93
	v_fmamk_f32 v92, v92, 0x3c800000, v127
	v_cmp_gt_f32_e64 s[8:9], s23, v92
	v_mul_f32_e32 v93, 0x4b800000, v92
	s_nop 0
	v_cndmask_b32_e64 v92, v92, v93, s[8:9]
	v_rsq_f32_e32 v92, v92
	s_nop 0
	v_mul_f32_e32 v93, 0x45800000, v92
	v_cndmask_b32_e64 v92, v92, v93, s[8:9]
	v_add_u32_e32 v93, 0xb000, v123
	v_pk_mul_f32 v[120:121], v[120:121], v[92:93] op_sel_hi:[1,0]
	v_pk_mul_f32 v[102:103], v[102:103], v[92:93] op_sel_hi:[1,0]
	s_waitcnt vmcnt(20)
	v_pk_fma_f32 v[80:81], v[80:81], v[120:121], v[84:85]
	s_waitcnt lgkmcnt(0)
	v_lshlrev_b32_e32 v84, 16, v142
	v_and_b32_e32 v85, 0xffff0000, v142
	v_pk_fma_f32 v[82:83], v[82:83], v[102:103], v[86:87]
	v_mul_f32_e32 v86, 0xbfb8aa3b, v84
	v_mul_f32_e32 v87, 0xbfb8aa3b, v85
	v_exp_f32_e32 v86, v86
	v_exp_f32_e32 v87, v87
	ds_read2_b64 v[138:141], v93 offset0:128 offset1:132
	v_pk_mul_f32 v[100:101], v[100:101], v[92:93] op_sel_hi:[1,0]
	v_add_f32_e32 v86, 1.0, v86
	v_add_f32_e32 v87, 1.0, v87
	v_rcp_f32_e32 v86, v86
	v_rcp_f32_e32 v87, v87
	s_waitcnt lgkmcnt(0)
	v_lshlrev_b32_e32 v146, 16, v138
	v_and_b32_e32 v147, 0xffff0000, v138
	v_pk_fma_f32 v[80:81], v[118:119], v[146:147], v[80:81] op_sel_hi:[0,1,1]
	v_pk_mul_f32 v[84:85], v[86:87], v[84:85]
	v_pk_mul_f32 v[98:99], v[98:99], v[92:93] op_sel_hi:[1,0]
	v_pk_mul_f32 v[80:81], v[84:85], v[80:81]
	v_lshlrev_b32_e32 v84, 16, v143
	v_and_b32_e32 v85, 0xffff0000, v143
	v_mul_f32_e32 v86, 0xbfb8aa3b, v84
	v_mul_f32_e32 v87, 0xbfb8aa3b, v85
	s_waitcnt vmcnt(18)
	v_pk_fma_f32 v[72:73], v[72:73], v[100:101], v[76:77]
	v_lshlrev_b32_e32 v76, 16, v144
	v_and_b32_e32 v77, 0xffff0000, v144
	v_exp_f32_e32 v86, v86
	v_exp_f32_e32 v87, v87
	v_pk_fma_f32 v[74:75], v[74:75], v[98:99], v[78:79]
	v_mul_f32_e32 v78, 0xbfb8aa3b, v76
	v_mul_f32_e32 v79, 0xbfb8aa3b, v77
	v_exp_f32_e32 v78, v78
	v_exp_f32_e32 v79, v79
	v_add_f32_e32 v86, 1.0, v86
	v_add_f32_e32 v87, 1.0, v87
	v_rcp_f32_e32 v86, v86
	v_rcp_f32_e32 v87, v87
	v_add_f32_e32 v78, 1.0, v78
	v_add_f32_e32 v79, 1.0, v79
	v_rcp_f32_e32 v78, v78
	v_rcp_f32_e32 v79, v79
	v_pk_mul_f32 v[84:85], v[86:87], v[84:85]
	v_lshlrev_b32_e32 v86, 16, v140
	v_and_b32_e32 v87, 0xffff0000, v140
	v_pk_fma_f32 v[72:73], v[118:119], v[86:87], v[72:73] op_sel_hi:[0,1,1]
	v_pk_mul_f32 v[76:77], v[78:79], v[76:77]
	v_lshlrev_b32_e32 v138, 16, v139
	v_pk_mul_f32 v[72:73], v[76:77], v[72:73]
	v_lshlrev_b32_e32 v76, 16, v145
	v_and_b32_e32 v77, 0xffff0000, v145
	v_mul_f32_e32 v78, 0xbfb8aa3b, v76
	v_mul_f32_e32 v79, 0xbfb8aa3b, v77
	v_exp_f32_e32 v78, v78
	v_exp_f32_e32 v79, v79
	v_and_b32_e32 v139, 0xffff0000, v139
	v_lshlrev_b32_e32 v102, 16, v141
	v_add_f32_e32 v78, 1.0, v78
	v_add_f32_e32 v79, 1.0, v79
	v_rcp_f32_e32 v78, v78
	v_rcp_f32_e32 v79, v79
	v_and_b32_e32 v103, 0xffff0000, v141
	v_pk_fma_f32 v[82:83], v[118:119], v[138:139], v[82:83] op_sel_hi:[0,1,1]
	v_pk_fma_f32 v[74:75], v[118:119], v[102:103], v[74:75] op_sel_hi:[0,1,1]
	v_pk_mul_f32 v[76:77], v[78:79], v[76:77]
	v_pk_mul_f32 v[82:83], v[84:85], v[82:83]
	v_pk_mul_f32 v[74:75], v[76:77], v[74:75]
	v_cvt_pk_bf16_f32 v84, v80, v81
	v_cvt_pk_bf16_f32 v85, v82, v83
	v_cvt_pk_bf16_f32 v72, v72, v73
	v_cvt_pk_bf16_f32 v73, v74, v75
	ds_read2_b64 v[80:83], v93 offset0:136 offset1:140
	ds_write2_b64 v106, v[84:85], v[72:73] offset1:4
	ds_read2_b64 v[72:75], v137 offset0:8 offset1:12
	v_pk_mul_f32 v[84:85], v[96:97], v[92:93] op_sel_hi:[1,0]
	s_waitcnt lgkmcnt(2)
	v_lshlrev_b32_e32 v76, 16, v80
	v_and_b32_e32 v77, 0xffff0000, v80
	v_lshlrev_b32_e32 v78, 16, v81
	v_and_b32_e32 v79, 0xffff0000, v81
	v_pk_mul_f32 v[80:81], v[94:95], v[92:93] op_sel_hi:[1,0]
	s_waitcnt vmcnt(16)
	v_pk_fma_f32 v[64:65], v[64:65], v[84:85], v[68:69]
	s_waitcnt lgkmcnt(0)
	v_lshlrev_b32_e32 v68, 16, v72
	v_and_b32_e32 v69, 0xffff0000, v72
	v_pk_fma_f32 v[66:67], v[66:67], v[80:81], v[70:71]
	v_mul_f32_e32 v70, 0xbfb8aa3b, v68
	v_mul_f32_e32 v71, 0xbfb8aa3b, v69
	v_exp_f32_e32 v70, v70
	v_exp_f32_e32 v71, v71
	v_pk_fma_f32 v[64:65], v[118:119], v[76:77], v[64:65] op_sel_hi:[0,1,1]
	v_pk_fma_f32 v[66:67], v[118:119], v[78:79], v[66:67] op_sel_hi:[0,1,1]
	v_add_f32_e32 v70, 1.0, v70
	v_add_f32_e32 v71, 1.0, v71
	v_rcp_f32_e32 v70, v70
	v_rcp_f32_e32 v71, v71
	s_nop 0
	v_pk_mul_f32 v[68:69], v[70:71], v[68:69]
	s_nop 0
	v_pk_mul_f32 v[64:65], v[68:69], v[64:65]
	v_lshlrev_b32_e32 v68, 16, v73
	v_and_b32_e32 v69, 0xffff0000, v73
	v_mul_f32_e32 v70, 0xbfb8aa3b, v68
	v_mul_f32_e32 v71, 0xbfb8aa3b, v69
	v_exp_f32_e32 v70, v70
	v_exp_f32_e32 v71, v71
	v_pk_mul_f32 v[72:73], v[88:89], v[92:93] op_sel_hi:[1,0]
	v_cvt_pk_bf16_f32 v64, v64, v65
	v_add_f32_e32 v70, 1.0, v70
	v_add_f32_e32 v71, 1.0, v71
	v_rcp_f32_e32 v70, v70
	v_rcp_f32_e32 v71, v71
	s_waitcnt vmcnt(14)
	v_pk_fma_f32 v[56:57], v[56:57], v[72:73], v[60:61]
	v_lshlrev_b32_e32 v60, 16, v74
	v_and_b32_e32 v61, 0xffff0000, v74
	v_pk_mul_f32 v[68:69], v[70:71], v[68:69]
	v_pk_mul_f32 v[70:71], v[90:91], v[92:93] op_sel_hi:[1,0]
	v_pk_mul_f32 v[66:67], v[68:69], v[66:67]
	v_pk_fma_f32 v[58:59], v[58:59], v[70:71], v[62:63]
	v_mul_f32_e32 v62, 0xbfb8aa3b, v60
	v_mul_f32_e32 v63, 0xbfb8aa3b, v61
	v_exp_f32_e32 v62, v62
	v_exp_f32_e32 v63, v63
	v_cvt_pk_bf16_f32 v65, v66, v67
	v_lshlrev_b32_e32 v66, 16, v82
	v_add_f32_e32 v62, 1.0, v62
	v_add_f32_e32 v63, 1.0, v63
	v_rcp_f32_e32 v62, v62
	v_rcp_f32_e32 v63, v63
	v_and_b32_e32 v67, 0xffff0000, v82
	v_pk_fma_f32 v[56:57], v[118:119], v[66:67], v[56:57] op_sel_hi:[0,1,1]
	v_lshlrev_b32_e32 v68, 16, v83
	v_pk_mul_f32 v[60:61], v[62:63], v[60:61]
	v_and_b32_e32 v69, 0xffff0000, v83
	v_pk_mul_f32 v[56:57], v[60:61], v[56:57]
	v_lshlrev_b32_e32 v60, 16, v75
	v_and_b32_e32 v61, 0xffff0000, v75
	v_mul_f32_e32 v62, 0xbfb8aa3b, v60
	v_mul_f32_e32 v63, 0xbfb8aa3b, v61
	v_exp_f32_e32 v62, v62
	v_exp_f32_e32 v63, v63
	v_pk_fma_f32 v[58:59], v[118:119], v[68:69], v[58:59] op_sel_hi:[0,1,1]
	v_cvt_pk_bf16_f32 v56, v56, v57
	v_add_f32_e32 v62, 1.0, v62
	v_add_f32_e32 v63, 1.0, v63
	v_rcp_f32_e32 v62, v62
	v_rcp_f32_e32 v63, v63
	s_nop 0
	v_pk_mul_f32 v[60:61], v[62:63], v[60:61]
	s_nop 0
	v_pk_mul_f32 v[58:59], v[60:61], v[58:59]
	v_or_b32_e32 v60, v135, v111
	v_cvt_pk_bf16_f32 v57, v58, v59
	ds_write2_b64 v106, v[64:65], v[56:57] offset0:8 offset1:12
	s_waitcnt lgkmcnt(0)
	s_barrier
; #define LDS_BARRIER() do { asm volatile("s_waitcnt lgkmcnt(0)" ::: "memory"); __builtin_amdgcn_s_barrier(); asm volatile("" ::: "memory"); } while (0)
; __device__ __forceinline__ void phase_out(const Params& p, unsigned char* shm) {
;     ...
; #pragma unroll
;         for (int i = 0; i < 2; ++i) { const int r = crow + 32 * i; *(u32x4*)(p.ACT + (size_t)(row0 + r) * DM + 1024 + h * 64 + cseg) = *(const u32x4*)(YVt + r * LD + cseg); }
;         LDS_BARRIER();
;     }
	s_load_dwordx2 s[8:9], s[0:1], 0xc8
	ds_read_b128 v[56:59], v125 offset:36864
	v_ashrrev_i32_e32 v61, 31, v60
	v_lshlrev_b64 v[60:61], 12, v[60:61]
	v_lshlrev_b32_e32 v106, 7, v136
	s_waitcnt lgkmcnt(0)
	v_lshl_add_u64 v[60:61], s[8:9], 0, v[60:61]
	v_lshl_add_u64 v[60:61], v[60:61], 0, v[106:107]
	v_lshl_add_u64 v[60:61], v[60:61], 0, v[116:117]
	global_store_dwordx4 v[60:61], v[56:59], off offset:2048
	v_or_b32_e32 v60, v135, v105
	ds_read_b128 v[56:59], v125 offset:41472
	v_ashrrev_i32_e32 v61, 31, v60
	v_lshlrev_b64 v[60:61], 12, v[60:61]
	v_lshl_add_u64 v[60:61], s[8:9], 0, v[60:61]
	v_lshl_add_u64 v[60:61], v[60:61], 0, v[106:107]
	v_lshl_add_u64 v[60:61], v[60:61], 0, v[116:117]
	s_waitcnt lgkmcnt(0)
	global_store_dwordx4 v[60:61], v[56:59], off offset:2048
	s_waitcnt lgkmcnt(0)
	s_barrier
	s_mov_b32 s8, s24
	s_cbranch_vccnz .LBB0_498
	s_cmp_lg_u32 s86, 0
	s_cbranch_scc1 .LBB0_499
	s_barrier
